# every P0 store (logf, ssq zeroing, masked spatial weights too) written through sc0 sc1: the write-back at the P0->P1 seam finds nothing dirty
# speedup vs baseline: 1.0048x; 1.0005x over previous
; __device__ __forceinline__ unsigned f2bf(float f) { unsigned u = __builtin_bit_cast(unsigned, f); return (u + 0x7fffu + ((u >> 16) & 1u)) >> 16; }
; __device__ __forceinline__ void p0_prologue(const Args& a, LAS unsigned char* lds, int vcu, int G, int tid, int lane, int wave) {
;     ...
;     for (int i = gt; i < 8 * 128 * 128; i += NGT) { const int s = i & 127, t = (i >> 7) & 127; const float v = ((t >> 6) >= (s >> 6)) ? w_sp[i] : 0.f; WSM[i] = (bf16)f2bf(v); }
.LBB0_43:
	s_or_b64 exec, exec, s[12:13]
	s_waitcnt vmcnt(0)
	v_bfe_u32 v8, v3, 16, 1
	v_add_u32_e32 v1, s4, v1
	v_add3_u32 v3, v3, v8, s5
	v_cmp_lt_i32_e32 vcc, s14, v1
	global_store_short_d16_hi v[6:7], v3, off sc0 sc1
	v_lshl_add_u64 v[4:5], v[4:5], 0, s[6:7]
	s_or_b64 s[10:11], vcc, s[10:11]
	v_lshl_add_u64 v[6:7], v[6:7], 0, s[8:9]
	s_andn2_b64 exec, exec, s[10:11]
	s_cbranch_execz .LBB0_46

; __device__ __forceinline__ void p0_prologue(const Args& a, LAS unsigned char* lds, int vcu, int G, int tid, int lane, int wave) {
;     ...
;     for (int i = gt; i < T; i += NGT) ssq[i] = 0.f;
.LBB0_49:
	v_add_u32_e32 v8, -2, v8
	v_ashrrev_i32_e32 v11, 31, v5
	v_mov_b32_e32 v10, v5
	v_ashrrev_i32_e32 v13, 31, v4
	v_mov_b32_e32 v12, v4
	v_cmp_eq_u32_e32 vcc, 0, v8
	v_add_u32_e32 v5, s10, v5
	v_add_u32_e32 v4, s5, v4
	v_lshl_add_u64 v[12:13], v[12:13], 2, s[28:29]
	v_lshl_add_u64 v[10:11], v[10:11], 2, s[28:29]
	s_or_b64 s[8:9], vcc, s[8:9]
	global_store_dword v[12:13], v7, off sc0 sc1
	global_store_dword v[10:11], v7, off sc0 sc1
	s_andn2_b64 exec, exec, s[8:9]
	s_cbranch_execnz .LBB0_49
	s_or_b64 exec, exec, s[8:9]
	v_mad_u64_u32 v[2:3], s[8:9], v6, s4, v[2:3]
	v_cmp_ne_u32_e32 vcc, v1, v6
	s_orn2_b64 s[8:9], vcc, exec

; __device__ __forceinline__ void p0_prologue(const Args& a, LAS unsigned char* lds, int vcu, int G, int tid, int lane, int wave) {
;     ...
;     for (int i = gt; i < T; i += NGT) ssq[i] = 0.f;
.LBB0_53:
	v_add_u32_e32 v2, s4, v2
	v_cmp_lt_i32_e32 vcc, s5, v2
	global_store_dword v[4:5], v1, off sc0 sc1
	s_or_b64 s[8:9], vcc, s[8:9]
	v_lshl_add_u64 v[4:5], v[4:5], 0, s[0:1]
	s_andn2_b64 exec, exec, s[8:9]
	s_cbranch_execnz .LBB0_53

; #define GAS __attribute__((address_space(1)))
; #define LAS __attribute__((address_space(3)))
; __device__ __forceinline__ unsigned pk2(float lo, float hi) { return pg8::cvt_pk_bf16_c(lo, hi); }
; __device__ __forceinline__ void p0_prologue(const Args& a, LAS unsigned char* lds, int vcu, int G, int tid, int lane, int wave) {
;     ...
;     for (int m = gw; m < T; m += NGW) {
;         f32x4 v[4]; float s2 = 0.f;
; #pragma unroll
;         for (int j = 0; j < 4; ++j) { v[j] = nv[j]; s2 += (v[j].x * v[j].x + v[j].y * v[j].y) + (v[j].z * v[j].z + v[j].w * v[j].w); }
;         if (m + NGW < T) { const GAS f32x4* xr = (const GAS f32x4*)(x + (size_t)(m + NGW) * DM) + lane;
; #pragma unroll
;             for (int j = 0; j < 4; ++j) nv[j] = xr[64 * j]; }
;         const float rstd = 1.0f / sqrtf(wave_sum(s2) * (1.f / DM) + EPS);
; #pragma unroll
;         for (int j = 0; j < 4; ++j) v[j] = v[j] * rstd * gv[j];
;         GAS unsigned long long* o8 = (GAS unsigned long long*)(XN + (size_t)m * DM) + lane;
; #pragma unroll
;         for (int j = 0; j < 4; ++j) o8[64 * j] = (unsigned long long)pk2(v[j].x, v[j].y) | ((unsigned long long)pk2(v[j].z, v[j].w) << 32);
;         float f[8];
; #pragma unroll
;         for (int h = 0; h < 8; ++h) { float acc = 0.f;
; #pragma unroll
;             for (int j = 0; j < 4; ++j) { const f32x4 w = *(const LAS f32x4*)(wf + h * 1024 + 256 * j + 4 * lane); acc += (v[j].x * w.x + v[j].y * w.y) + (v[j].z * w.z + v[j].w * w.w); }
;             f[h] = wave_sum(acc); }
.LBB0_59:
	v_mul_f32_e32 v185, v175, v175
	v_mul_f32_e32 v186, v177, v177
	v_fmac_f32_e32 v185, v174, v174
	v_fmac_f32_e32 v186, v176, v176
	v_add_f32_e32 v185, v185, v186
	v_mul_f32_e32 v186, v171, v171
	v_mul_f32_e32 v187, v173, v173
	v_fmac_f32_e32 v186, v170, v170
	v_fmac_f32_e32 v187, v172, v172
	v_add_f32_e32 v186, v186, v187
	v_add_f32_e32 v185, v186, v185
	v_mul_f32_e32 v186, v167, v167
	v_mul_f32_e32 v187, v169, v169
	v_fmac_f32_e32 v186, v166, v166
	v_fmac_f32_e32 v187, v168, v168
	v_add_f32_e32 v186, v186, v187
	v_add_f32_e32 v185, v186, v185
	v_mul_f32_e32 v186, v163, v163
	v_mul_f32_e32 v187, v165, v165
	v_fmac_f32_e32 v186, v162, v162
	v_fmac_f32_e32 v187, v164, v164
	v_add_f32_e32 v186, v186, v187
	v_add_f32_e32 v185, v186, v185
	ds_bpermute_b32 v186, v1, v185
	s_waitcnt lgkmcnt(0)
	v_add_f32_e32 v185, v185, v186
	ds_bpermute_b32 v186, v189, v185
	s_waitcnt lgkmcnt(0)
	v_add_f32_e32 v185, v185, v186
	ds_bpermute_b32 v186, v190, v185
	s_waitcnt lgkmcnt(0)
	v_add_f32_e32 v185, v185, v186
	ds_bpermute_b32 v186, v191, v185
	s_waitcnt lgkmcnt(0)
	v_add_f32_e32 v185, v185, v186
	ds_bpermute_b32 v186, v192, v185
	s_waitcnt lgkmcnt(0)
	v_add_f32_e32 v185, v185, v186
	ds_bpermute_b32 v186, v193, v185
	s_waitcnt lgkmcnt(0)
	v_add_f32_e32 v185, v185, v186
	v_fmamk_f32 v185, v185, 0x3a800000, v194
	v_mul_f32_e32 v186, 0x4f800000, v185
	v_cmp_gt_f32_e32 vcc, s33, v185
	s_nop 1
	v_cndmask_b32_e32 v185, v185, v186, vcc
	v_sqrt_f32_e32 v186, v185
	s_nop 0
	v_add_u32_e32 v187, -1, v186
	v_add_u32_e32 v198, 1, v186
	v_fma_f32 v199, -v187, v186, v185
	v_fma_f32 v200, -v198, v186, v185
	v_cmp_ge_f32_e64 s[18:19], 0, v199
	s_nop 1
	v_cndmask_b32_e64 v186, v186, v187, s[18:19]
	v_cmp_lt_f32_e64 s[18:19], 0, v200
	s_nop 1
	v_cndmask_b32_e64 v186, v186, v198, s[18:19]
	v_mul_f32_e32 v187, 0x37800000, v186
	v_cndmask_b32_e32 v186, v186, v187, vcc
	v_cmp_class_f32_e32 vcc, v185, v195
	s_nop 1
	v_cndmask_b32_e32 v185, v186, v185, vcc
	v_div_scale_f32 v186, s[18:19], v185, v185, 1.0
	v_rcp_f32_e32 v187, v186
	v_div_scale_f32 v198, vcc, 1.0, v185, 1.0
	v_fma_f32 v199, -v186, v187, 1.0
	v_fmac_f32_e32 v187, v199, v187
	v_mul_f32_e32 v199, v198, v187
	v_fma_f32 v200, -v186, v199, v198
	v_fmac_f32_e32 v199, v200, v187
	v_fma_f32 v186, -v186, v199, v198
	v_div_fmas_f32 v186, v186, v187, v199
	v_div_fixup_f32 v186, v186, v185, 1.0
	v_pk_mul_f32 v[198:199], v[174:175], v[186:187] op_sel_hi:[1,0]
	v_pk_mul_f32 v[174:175], v[176:177], v[186:187] op_sel_hi:[1,0]
	v_pk_mul_f32 v[176:177], v[2:3], v[198:199]
	v_pk_mul_f32 v[174:175], v[4:5], v[174:175]
	v_pk_mul_f32 v[198:199], v[166:167], v[186:187] op_sel_hi:[1,0]
	v_pk_mul_f32 v[200:201], v[170:171], v[186:187] op_sel_hi:[1,0]
	v_pk_mul_f32 v[170:171], v[172:173], v[186:187] op_sel_hi:[1,0]
	v_pk_mul_f32 v[166:167], v[168:169], v[186:187] op_sel_hi:[1,0]
	v_pk_mul_f32 v[168:169], v[10:11], v[198:199]
	v_pk_mul_f32 v[198:199], v[162:163], v[186:187] op_sel_hi:[1,0]
	v_pk_mul_f32 v[162:163], v[164:165], v[186:187] op_sel_hi:[1,0]
	v_mul_f32_e32 v185, v19, v177
	v_mul_f32_e32 v186, v21, v175
	v_pk_mul_f32 v[170:171], v[8:9], v[170:171]
	v_pk_mul_f32 v[172:173], v[6:7], v[200:201]
	v_fmac_f32_e32 v185, v18, v176
	v_fmac_f32_e32 v186, v20, v174
	v_add_f32_e32 v185, v185, v186
	v_mul_f32_e32 v186, v23, v173
	v_mul_f32_e32 v187, v25, v171
	v_fmac_f32_e32 v186, v22, v172
	v_fmac_f32_e32 v187, v24, v170
	v_pk_mul_f32 v[166:167], v[12:13], v[166:167]
	v_add_f32_e32 v185, 0, v185
	v_add_f32_e32 v186, v186, v187
	v_add_f32_e32 v185, v186, v185
	v_mul_f32_e32 v186, v27, v169
	v_mul_f32_e32 v187, v29, v167
	v_fmac_f32_e32 v186, v26, v168
	v_fmac_f32_e32 v187, v28, v166
	v_pk_mul_f32 v[162:163], v[16:17], v[162:163]
	v_pk_mul_f32 v[164:165], v[14:15], v[198:199]
	v_add_f32_e32 v186, v186, v187
	v_add_f32_e32 v185, v186, v185
	v_mul_f32_e32 v186, v31, v165
	v_mul_f32_e32 v187, v33, v163
	v_fmac_f32_e32 v186, v30, v164
	v_fmac_f32_e32 v187, v32, v162
	v_add_f32_e32 v186, v186, v187
	v_mul_f32_e32 v187, v177, v35
	v_mul_f32_e32 v198, v175, v37
	v_fmac_f32_e32 v187, v176, v34
	v_fmac_f32_e32 v198, v174, v36
	v_add_f32_e32 v187, v187, v198
	v_mul_f32_e32 v198, v173, v39
	v_mul_f32_e32 v199, v171, v41
	v_fmac_f32_e32 v198, v172, v38
	v_fmac_f32_e32 v199, v170, v40
	v_add_f32_e32 v187, 0, v187
	v_add_f32_e32 v198, v198, v199
	v_add_f32_e32 v187, v187, v198
	v_mul_f32_e32 v198, v169, v43
	v_mul_f32_e32 v199, v167, v45
	v_fmac_f32_e32 v198, v168, v42
	v_fmac_f32_e32 v199, v166, v44
	v_add_f32_e32 v198, v198, v199
	v_add_f32_e32 v187, v187, v198
	v_mul_f32_e32 v198, v165, v47
	v_mul_f32_e32 v199, v163, v49
	v_fmac_f32_e32 v198, v164, v46
	v_fmac_f32_e32 v199, v162, v48
	v_add_f32_e32 v198, v198, v199
	v_add_f32_e32 v185, v186, v185
	v_add_f32_e32 v187, v187, v198
	ds_bpermute_b32 v186, v1, v185
	ds_bpermute_b32 v198, v1, v187
	v_mul_f32_e32 v202, v175, v53
	v_fmac_f32_e32 v202, v174, v52
	v_mul_f32_e32 v203, v171, v57
	s_waitcnt lgkmcnt(1)
	v_add_f32_e32 v185, v185, v186
	s_waitcnt lgkmcnt(0)
	v_add_f32_e32 v198, v187, v198
	ds_bpermute_b32 v199, v189, v185
	ds_bpermute_b32 v200, v189, v198
	v_fmac_f32_e32 v203, v170, v56
	v_mul_f32_e32 v204, v175, v69
	v_fmac_f32_e32 v204, v174, v68
	s_waitcnt lgkmcnt(1)
	v_add_f32_e32 v185, v185, v199
	s_waitcnt lgkmcnt(0)
	v_add_f32_e32 v198, v198, v200
	ds_bpermute_b32 v199, v190, v185
	ds_bpermute_b32 v200, v190, v198
	v_mul_f32_e32 v205, v171, v73
	v_fmac_f32_e32 v205, v170, v72
	v_mul_f32_e32 v206, v175, v85
	s_waitcnt lgkmcnt(1)
	v_add_f32_e32 v185, v185, v199
	s_waitcnt lgkmcnt(0)
	v_add_f32_e32 v198, v198, v200
	ds_bpermute_b32 v199, v191, v185
	ds_bpermute_b32 v200, v191, v198
	v_fmac_f32_e32 v206, v174, v84
	v_mul_f32_e32 v207, v171, v89
	v_fmac_f32_e32 v207, v170, v88
	s_waitcnt lgkmcnt(1)
; #define GAS __attribute__((address_space(1)))
; #define LAS __attribute__((address_space(3)))
; __device__ __forceinline__ unsigned pk2(float lo, float hi) { return pg8::cvt_pk_bf16_c(lo, hi); }
; __device__ __forceinline__ void p0_prologue(const Args& a, LAS unsigned char* lds, int vcu, int G, int tid, int lane, int wave) {
;     ...
;         GAS unsigned long long* o8 = (GAS unsigned long long*)(XN + (size_t)m * DM) + lane;
; #pragma unroll
;         for (int j = 0; j < 4; ++j) o8[64 * j] = (unsigned long long)pk2(v[j].x, v[j].y) | ((unsigned long long)pk2(v[j].z, v[j].w) << 32);
;         float f[8];
; #pragma unroll
;         for (int h = 0; h < 8; ++h) { float acc = 0.f;
; #pragma unroll
;             for (int j = 0; j < 4; ++j) { const f32x4 w = *(const LAS f32x4*)(wf + h * 1024 + 256 * j + 4 * lane); acc += (v[j].x * w.x + v[j].y * w.y) + (v[j].z * w.z + v[j].w * w.w); }
;             f[h] = wave_sum(acc); }
	v_add_f32_e32 v185, v185, v199
	s_waitcnt lgkmcnt(0)
	v_add_f32_e32 v200, v198, v200
	ds_bpermute_b32 v199, v192, v185
	ds_bpermute_b32 v201, v192, v200
	v_mul_f32_e32 v208, v175, v101
	v_fmac_f32_e32 v208, v174, v100
	v_mul_f32_e32 v209, v171, v105
	s_waitcnt lgkmcnt(1)
	v_add_f32_e32 v185, v185, v199
	s_waitcnt lgkmcnt(0)
	v_add_f32_e32 v199, v200, v201
	v_mul_f32_e32 v201, v177, v51
	v_fmac_f32_e32 v201, v176, v50
	v_add_f32_e32 v201, v201, v202
	v_mul_f32_e32 v202, v173, v55
	v_fmac_f32_e32 v202, v172, v54
	v_add_f32_e32 v201, 0, v201
	v_add_f32_e32 v202, v202, v203
	v_add_f32_e32 v201, v201, v202
	v_mul_f32_e32 v202, v169, v59
	v_mul_f32_e32 v203, v167, v61
	v_fmac_f32_e32 v202, v168, v58
	v_fmac_f32_e32 v203, v166, v60
	v_add_f32_e32 v202, v202, v203
	v_add_f32_e32 v201, v201, v202
	v_mul_f32_e32 v202, v165, v63
	v_mul_f32_e32 v203, v163, v65
	v_fmac_f32_e32 v202, v164, v62
	v_fmac_f32_e32 v203, v162, v64
	v_add_f32_e32 v202, v202, v203
	v_mul_f32_e32 v203, v177, v67
	v_fmac_f32_e32 v203, v176, v66
	v_add_f32_e32 v203, v203, v204
	v_mul_f32_e32 v204, v173, v71
	v_fmac_f32_e32 v204, v172, v70
	v_add_f32_e32 v203, 0, v203
	v_add_f32_e32 v204, v204, v205
	v_add_f32_e32 v203, v203, v204
	v_mul_f32_e32 v204, v169, v75
	v_mul_f32_e32 v205, v167, v77
	v_fmac_f32_e32 v204, v168, v74
	v_fmac_f32_e32 v205, v166, v76
	v_add_f32_e32 v204, v204, v205
	v_add_f32_e32 v203, v203, v204
	v_mul_f32_e32 v204, v165, v79
	v_mul_f32_e32 v205, v163, v81
	v_fmac_f32_e32 v204, v164, v78
	v_fmac_f32_e32 v205, v162, v80
	v_add_f32_e32 v204, v204, v205
	v_mul_f32_e32 v205, v177, v83
	v_fmac_f32_e32 v205, v176, v82
	v_add_f32_e32 v205, v205, v206
	v_mul_f32_e32 v206, v173, v87
	v_fmac_f32_e32 v206, v172, v86
	v_add_f32_e32 v205, 0, v205
	v_add_f32_e32 v206, v206, v207
	v_add_f32_e32 v205, v205, v206
	v_mul_f32_e32 v206, v169, v91
	v_mul_f32_e32 v207, v167, v93
	v_fmac_f32_e32 v206, v168, v90
	v_fmac_f32_e32 v207, v166, v92
	v_add_f32_e32 v206, v206, v207
	v_add_f32_e32 v205, v205, v206
	v_mul_f32_e32 v206, v165, v95
	v_mul_f32_e32 v207, v163, v97
	v_fmac_f32_e32 v206, v164, v94
	v_fmac_f32_e32 v207, v162, v96
	v_add_f32_e32 v206, v206, v207
	v_mul_f32_e32 v207, v177, v99
	v_fmac_f32_e32 v207, v176, v98
	v_add_f32_e32 v207, v207, v208
	v_mul_f32_e32 v208, v173, v103
	v_fmac_f32_e32 v208, v172, v102
	v_fmac_f32_e32 v209, v170, v104
	v_add_f32_e32 v207, 0, v207
	v_add_f32_e32 v208, v208, v209
	v_add_f32_e32 v207, v207, v208
	v_mul_f32_e32 v208, v169, v107
	v_mul_f32_e32 v209, v167, v109
	v_fmac_f32_e32 v208, v168, v106
	v_fmac_f32_e32 v209, v166, v108
	v_add_f32_e32 v208, v208, v209
	v_add_f32_e32 v207, v207, v208
	v_mul_f32_e32 v208, v165, v111
	v_mul_f32_e32 v209, v163, v113
	v_fmac_f32_e32 v208, v164, v110
	v_fmac_f32_e32 v209, v162, v112
	v_add_f32_e32 v208, v208, v209
	v_mul_f32_e32 v209, v177, v115
	v_mul_f32_e32 v210, v175, v117
	v_fmac_f32_e32 v209, v176, v114
	v_fmac_f32_e32 v210, v174, v116
	v_add_f32_e32 v209, v209, v210
	v_mul_f32_e32 v210, v173, v119
	v_mul_f32_e32 v211, v171, v121
	v_fmac_f32_e32 v210, v172, v118
	v_fmac_f32_e32 v211, v170, v120
	v_cvt_pk_bf16_f32 v186, v176, v177
	v_cvt_pk_bf16_f32 v187, v174, v175
	v_add_f32_e32 v209, 0, v209
	v_add_f32_e32 v210, v210, v211
	global_store_dwordx2 v[180:181], v[186:187], off sc0 sc1
	v_cvt_pk_bf16_f32 v186, v172, v173
	v_cvt_pk_bf16_f32 v187, v170, v171
	v_add_f32_e32 v209, v209, v210
	v_mul_f32_e32 v210, v169, v123
	v_mul_f32_e32 v211, v167, v125
	v_mul_f32_e32 v177, v177, v131
	v_mul_f32_e32 v175, v175, v133
	global_store_dwordx2 v[180:181], v[186:187], off offset:512 sc0 sc1
	v_cvt_pk_bf16_f32 v186, v168, v169
	v_cvt_pk_bf16_f32 v187, v166, v167
	v_fmac_f32_e32 v210, v168, v122
	v_fmac_f32_e32 v211, v166, v124
	v_fmac_f32_e32 v177, v176, v130
	v_fmac_f32_e32 v175, v174, v132
	v_mul_f32_e32 v173, v173, v135
	v_mul_f32_e32 v171, v171, v137
	v_mul_f32_e32 v169, v169, v139
	v_mul_f32_e32 v167, v167, v141
	v_add_f32_e32 v210, v210, v211
	v_add_f32_e32 v174, v177, v175
	v_fmac_f32_e32 v173, v172, v134
	v_fmac_f32_e32 v171, v170, v136
	v_fmac_f32_e32 v169, v168, v138
	v_fmac_f32_e32 v167, v166, v140
	v_add_f32_e32 v209, v209, v210
	v_mul_f32_e32 v210, v165, v127
	v_mul_f32_e32 v211, v163, v129
	v_add_f32_e32 v174, 0, v174
	v_add_f32_e32 v170, v173, v171
	v_add_f32_e32 v166, v169, v167
	v_mul_f32_e32 v167, v165, v143
	v_mul_f32_e32 v168, v163, v145
	v_fmac_f32_e32 v210, v164, v126
	v_fmac_f32_e32 v211, v162, v128
	v_add_f32_e32 v170, v174, v170
	v_fmac_f32_e32 v167, v164, v142
	v_fmac_f32_e32 v168, v162, v144
	v_add_f32_e32 v210, v210, v211
	v_add_f32_e32 v166, v170, v166
	v_add_f32_e32 v167, v167, v168
	v_add_f32_e32 v201, v201, v202
	v_add_f32_e32 v203, v203, v204
	v_add_f32_e32 v205, v205, v206
	v_add_f32_e32 v207, v207, v208
	v_add_f32_e32 v209, v209, v210
	v_add_f32_e32 v166, v166, v167
	ds_bpermute_b32 v202, v1, v201
	ds_bpermute_b32 v204, v1, v203
	ds_bpermute_b32 v206, v1, v205
	ds_bpermute_b32 v208, v1, v207
	ds_bpermute_b32 v210, v1, v209
	ds_bpermute_b32 v167, v1, v166
	s_waitcnt lgkmcnt(5)
	v_add_f32_e32 v201, v201, v202
	s_waitcnt lgkmcnt(4)
	v_add_f32_e32 v203, v203, v204
	s_waitcnt lgkmcnt(3)
	v_add_f32_e32 v205, v205, v206
	s_waitcnt lgkmcnt(2)
	v_add_f32_e32 v168, v207, v208
	s_waitcnt lgkmcnt(1)
	v_add_f32_e32 v170, v209, v210
	s_waitcnt lgkmcnt(0)
	v_add_f32_e32 v166, v166, v167
	ds_bpermute_b32 v202, v189, v201
	ds_bpermute_b32 v204, v189, v203
	ds_bpermute_b32 v206, v189, v205
	ds_bpermute_b32 v169, v189, v168
	ds_bpermute_b32 v171, v189, v170
	ds_bpermute_b32 v167, v189, v166
	s_waitcnt lgkmcnt(5)
	v_add_f32_e32 v201, v201, v202
	s_waitcnt lgkmcnt(4)
	v_add_f32_e32 v203, v203, v204
	s_waitcnt lgkmcnt(3)
; #define LAS __attribute__((address_space(3)))
; __device__ __forceinline__ unsigned pk2(float lo, float hi) { return pg8::cvt_pk_bf16_c(lo, hi); }
; __device__ __forceinline__ void p0_prologue(const Args& a, LAS unsigned char* lds, int vcu, int G, int tid, int lane, int wave) {
;     ...
;         for (int j = 0; j < 4; ++j) o8[64 * j] = (unsigned long long)pk2(v[j].x, v[j].y) | ((unsigned long long)pk2(v[j].z, v[j].w) << 32);
;         float f[8];
; #pragma unroll
;         for (int h = 0; h < 8; ++h) { float acc = 0.f;
; #pragma unroll
;             for (int j = 0; j < 4; ++j) { const f32x4 w = *(const LAS f32x4*)(wf + h * 1024 + 256 * j + 4 * lane); acc += (v[j].x * w.x + v[j].y * w.y) + (v[j].z * w.z + v[j].w * w.w); }
;             f[h] = wave_sum(acc); }
;         float fz = f[0];
; #pragma unroll
;         for (int h = 1; h < 8; ++h) fz = (lane == h) ? f[h] : fz;
;         if (lane < 8) { const float z = fz + b_f[lane]; const float ls = fminf(z, 0.f) - log1pf(expf(-fabsf(z)));
	v_add_f32_e32 v205, v205, v206
	s_waitcnt lgkmcnt(2)
	v_add_f32_e32 v168, v168, v169
	s_waitcnt lgkmcnt(1)
	v_add_f32_e32 v170, v170, v171
	s_waitcnt lgkmcnt(0)
	v_add_f32_e32 v166, v166, v167
	ds_bpermute_b32 v202, v190, v201
	ds_bpermute_b32 v204, v190, v203
	ds_bpermute_b32 v206, v190, v205
	ds_bpermute_b32 v169, v190, v168
	ds_bpermute_b32 v171, v190, v170
	ds_bpermute_b32 v167, v190, v166
	s_waitcnt lgkmcnt(5)
	v_add_f32_e32 v201, v201, v202
	s_waitcnt lgkmcnt(4)
	v_add_f32_e32 v203, v203, v204
	s_waitcnt lgkmcnt(3)
	v_add_f32_e32 v205, v205, v206
	s_waitcnt lgkmcnt(2)
	v_add_f32_e32 v168, v168, v169
	s_waitcnt lgkmcnt(1)
	v_add_f32_e32 v170, v170, v171
	s_waitcnt lgkmcnt(0)
	v_add_f32_e32 v166, v166, v167
	ds_bpermute_b32 v202, v191, v201
	ds_bpermute_b32 v204, v191, v203
	ds_bpermute_b32 v206, v191, v205
	ds_bpermute_b32 v169, v191, v168
	ds_bpermute_b32 v171, v191, v170
	ds_bpermute_b32 v167, v191, v166
	s_waitcnt lgkmcnt(5)
	v_add_f32_e32 v201, v201, v202
	s_waitcnt lgkmcnt(4)
	v_add_f32_e32 v203, v203, v204
	s_waitcnt lgkmcnt(3)
	v_add_f32_e32 v205, v205, v206
	s_waitcnt lgkmcnt(2)
	v_add_f32_e32 v168, v168, v169
	s_waitcnt lgkmcnt(1)
	v_add_f32_e32 v170, v170, v171
	s_waitcnt lgkmcnt(0)
	v_add_f32_e32 v172, v166, v167
	ds_bpermute_b32 v202, v192, v201
	ds_bpermute_b32 v204, v192, v203
	ds_bpermute_b32 v206, v192, v205
	ds_bpermute_b32 v169, v192, v168
	ds_bpermute_b32 v171, v192, v170
	ds_bpermute_b32 v173, v192, v172
	s_waitcnt lgkmcnt(5)
	v_add_f32_e32 v201, v201, v202
	s_waitcnt lgkmcnt(4)
	v_add_f32_e32 v203, v203, v204
	s_waitcnt lgkmcnt(3)
	v_add_f32_e32 v205, v205, v206
	s_waitcnt lgkmcnt(2)
	v_add_f32_e32 v166, v168, v169
	s_waitcnt lgkmcnt(1)
	v_add_f32_e32 v168, v170, v171
	s_waitcnt lgkmcnt(0)
	v_add_f32_e32 v170, v172, v173
	ds_bpermute_b32 v198, v193, v185
	ds_bpermute_b32 v200, v193, v199
	ds_bpermute_b32 v202, v193, v201
	ds_bpermute_b32 v204, v193, v203
	ds_bpermute_b32 v206, v193, v205
	ds_bpermute_b32 v167, v193, v166
	ds_bpermute_b32 v169, v193, v168
	ds_bpermute_b32 v171, v193, v170
	v_cvt_pk_bf16_f32 v164, v164, v165
	v_cvt_pk_bf16_f32 v165, v162, v163
	global_store_dwordx2 v[180:181], v[186:187], off offset:1024 sc0 sc1
	global_store_dwordx2 v[180:181], v[164:165], off offset:1536 sc0 sc1
	s_and_saveexec_b64 s[18:19], s[0:1]
	s_cbranch_execz .LBB0_56
; __device__ __forceinline__ void p0_prologue(const Args& a, LAS unsigned char* lds, int vcu, int G, int tid, int lane, int wave) {
;     ...
;         float fz = f[0];
; #pragma unroll
;         for (int h = 1; h < 8; ++h) fz = (lane == h) ? f[h] : fz;
;         if (lane < 8) { const float z = fz + b_f[lane]; const float ls = fminf(z, 0.f) - log1pf(expf(-fabsf(z)));
;             const int b = m >> 12, s = m & 4095; logf_[((size_t)(b * NH + lane) << 12) + s] = ls; }
	global_load_dword v164, v[178:179], off
	s_waitcnt lgkmcnt(0)
	v_add_f32_e32 v165, v170, v171
	v_add_f32_e32 v162, v199, v200
	v_add_f32_e32 v170, v185, v198
	v_add_f32_e32 v163, v201, v202
	v_cndmask_b32_e64 v170, v170, v162, s[14:15]
	v_add_f32_e32 v168, v168, v169
	v_add_f32_e32 v169, v203, v204
	v_cndmask_b32_e64 v170, v170, v163, s[12:13]
	v_add_f32_e32 v166, v166, v167
	v_add_f32_e32 v167, v205, v206
	v_cndmask_b32_e64 v169, v170, v169, s[10:11]
	v_cndmask_b32_e64 v167, v169, v167, s[8:9]
	v_cndmask_b32_e64 v166, v167, v166, s[6:7]
	v_cndmask_b32_e64 v166, v166, v168, s[4:5]
	v_cndmask_b32_e64 v165, v166, v165, s[16:17]
	s_and_b32 s38, s62, 0xfff
	s_ashr_i32 s62, s62, 9
	v_and_or_b32 v162, s62, -8, v188
	v_ashrrev_i32_e32 v163, 31, v162
	v_lshlrev_b64 v[162:163], 14, v[162:163]
	s_lshl_b32 s38, s38, 2
	v_lshl_add_u64 v[162:163], s[20:21], 0, v[162:163]
	v_lshl_add_u64 v[162:163], v[162:163], 0, s[38:39]
	s_waitcnt vmcnt(0)
	v_add_f32_e32 v164, v165, v164
	v_mul_f32_e64 v165, |v164|, s35
	v_fma_f32 v166, |v164|, s35, -v165
	v_rndne_f32_e32 v167, v165
	v_fma_f32 v166, |v164|, s54, v166
	v_sub_f32_e32 v165, v165, v167
	v_add_f32_e32 v165, v165, v166
	v_cvt_i32_f32_e32 v167, v167
	v_exp_f32_e32 v165, v165
	v_cmp_ngt_f32_e64 vcc, |v164|, s55
	v_min_f32_e32 v186, 0, v164
	v_ldexp_f32 v165, v165, v167
	v_cndmask_b32_e32 v165, 0, v165, vcc
	v_cmp_nlt_f32_e64 vcc, |v164|, s56
	s_nop 1
	v_cndmask_b32_e32 v187, v197, v165, vcc
	v_add_f32_e32 v166, 1.0, v187
	v_add_f32_e32 v167, -1.0, v166
	v_frexp_mant_f32_e32 v168, v166
	v_cvt_f64_f32_e32 v[164:165], v166
	v_sub_f32_e32 v169, v167, v166
	v_frexp_exp_i32_f64_e32 v164, v[164:165]
	v_cmp_gt_f32_e32 vcc, s58, v168
	v_sub_f32_e32 v167, v187, v167
	v_add_f32_e32 v165, 1.0, v169
	v_subbrev_co_u32_e32 v164, vcc, 0, v164, vcc
	v_add_f32_e32 v165, v167, v165
	v_sub_u32_e32 v167, 0, v164
	v_ldexp_f32 v166, v166, v167
	v_add_f32_e32 v168, -1.0, v166
	v_add_f32_e32 v169, 1.0, v166
	v_ldexp_f32 v165, v165, v167
	v_add_f32_e32 v167, 1.0, v168
	v_add_f32_e32 v170, -1.0, v169
	v_sub_f32_e32 v167, v166, v167
	v_sub_f32_e32 v166, v166, v170
	v_add_f32_e32 v170, v165, v167
	v_add_f32_e32 v165, v165, v166
	v_add_f32_e32 v172, v169, v165
	v_rcp_f32_e32 v173, v172
	v_add_f32_e32 v167, v168, v170
	v_sub_f32_e32 v168, v168, v167
	v_sub_f32_e32 v166, v169, v172
	v_mul_f32_e32 v175, v167, v173
	v_add_f32_e32 v174, v170, v168
	v_mul_f32_e32 v168, v172, v175
	v_add_f32_e32 v165, v165, v166
	v_fma_f32 v170, v175, v172, -v168
	v_fmac_f32_e32 v170, v175, v165
	v_add_f32_e32 v166, v168, v170
	v_sub_f32_e32 v169, v167, v166
	v_mov_b32_e32 v171, v166
	v_pk_add_f32 v[166:167], v[166:167], v[168:169] neg_lo:[0,1] neg_hi:[0,1]
	v_cvt_f32_i32_e32 v164, v164
	v_pk_add_f32 v[166:167], v[166:167], v[170:171] neg_lo:[0,1] neg_hi:[0,1]
	v_cmp_neq_f32_e32 vcc, s57, v187
	v_add_f32_e32 v167, v174, v167
	v_add_f32_e32 v166, v166, v167
	v_add_f32_e32 v167, v169, v166
	v_mul_f32_e32 v171, v173, v167
	v_mul_f32_e32 v168, v172, v171
	v_sub_f32_e32 v169, v169, v167
	v_add_f32_e32 v176, v175, v171
	v_fma_f32 v170, v171, v172, -v168
	v_add_f32_e32 v174, v166, v169
	v_sub_f32_e32 v166, v176, v175
	v_fmac_f32_e32 v170, v171, v165
	v_sub_f32_e32 v165, v171, v166
	v_add_f32_e32 v166, v168, v170
	v_sub_f32_e32 v169, v167, v166
	v_mov_b32_e32 v171, v166
	v_pk_add_f32 v[166:167], v[166:167], v[168:169] neg_lo:[0,1] neg_hi:[0,1]
	s_nop 0
	v_pk_add_f32 v[166:167], v[166:167], v[170:171] neg_lo:[0,1] neg_hi:[0,1]
	s_nop 0
	v_add_f32_e32 v167, v174, v167
	v_add_f32_e32 v166, v166, v167
	v_add_f32_e32 v166, v169, v166
	v_mul_f32_e32 v166, v173, v166
	v_add_f32_e32 v165, v165, v166
	v_add_f32_e32 v166, v176, v165
	v_mul_f32_e32 v168, v166, v166
	v_sub_f32_e32 v169, v166, v176
	v_fmamk_f32 v170, v168, 0x3e9b6dac, v196
	v_sub_f32_e32 v169, v165, v169
	v_mul_f32_e32 v165, v166, v168
	v_fmaak_f32 v185, v168, v170, 0x3f2aaada
	v_ldexp_f32 v171, v169, 1
	v_pk_mul_f32 v[168:169], v[164:165], v[184:185]
	v_ldexp_f32 v167, v166, 1
	v_fma_f32 v166, v164, s59, -v168
	v_fmac_f32_e32 v166, 0xb102e308, v164
	v_pk_add_f32 v[164:165], v[168:169], v[166:167]
	v_mov_b32_e32 v170, v168
	v_sub_f32_e32 v174, v165, v167
	v_pk_add_f32 v[172:173], v[164:165], v[168:169] neg_lo:[0,1] neg_hi:[0,1]
	v_sub_f32_e32 v168, v169, v174
	v_add_f32_e32 v171, v171, v168
	v_pk_add_f32 v[168:169], v[164:165], v[170:171]
	v_mov_b32_e32 v167, v164
	v_mov_b32_e32 v173, v169
	v_pk_add_f32 v[176:177], v[166:167], v[172:173] neg_lo:[0,1] neg_hi:[0,1]
	v_pk_add_f32 v[166:167], v[166:167], v[172:173]
	v_mov_b32_e32 v175, v164
	v_pk_add_f32 v[172:173], v[166:167], v[164:165] op_sel:[1,0] op_sel_hi:[0,1] neg_lo:[0,1] neg_hi:[0,1]
	v_mov_b32_e32 v174, v171
	v_mov_b32_e32 v170, v169
	v_mov_b32_e32 v171, v167
	v_pk_mov_b32 v[164:165], v[164:165], v[172:173] op_sel:[1,0]
	v_pk_add_f32 v[168:169], v[168:169], v[172:173] op_sel_hi:[1,0] neg_lo:[0,1] neg_hi:[0,1]
	v_pk_add_f32 v[164:165], v[170:171], v[164:165] neg_lo:[0,1] neg_hi:[0,1]
	v_mov_b32_e32 v168, v176
	v_pk_add_f32 v[164:165], v[174:175], v[164:165] neg_lo:[0,1] neg_hi:[0,1]
	v_mov_b32_e32 v177, v167
	v_pk_add_f32 v[168:169], v[168:169], v[164:165]
	s_nop 0
	v_pk_add_f32 v[170:171], v[168:169], v[168:169] op_sel:[0,1] op_sel_hi:[1,0]
	s_nop 0
	v_pk_add_f32 v[166:167], v[166:167], v[170:171] op_sel:[1,0] op_sel_hi:[0,1]
	v_mov_b32_e32 v169, v166
	v_mov_b32_e32 v165, v170
	v_pk_add_f32 v[170:171], v[168:169], v[176:177] neg_lo:[0,1] neg_hi:[0,1]
	s_nop 0
	v_sub_f32_e32 v167, v168, v170
	v_pk_add_f32 v[164:165], v[164:165], v[170:171] neg_lo:[0,1] neg_hi:[0,1]
	v_sub_f32_e32 v167, v176, v167
	v_add_f32_e32 v164, v164, v167
	v_add_f32_e32 v164, v164, v165
	v_add_f32_e32 v164, v166, v164
	v_cndmask_b32_e32 v164, v197, v164, vcc
	v_cmp_lt_f32_e64 vcc, |v187|, s63
	s_nop 1
	v_cndmask_b32_e32 v164, v164, v187, vcc
	v_sub_f32_e32 v164, v186, v164
	global_store_dword v[162:163], v164, off sc0 sc1
	s_branch .LBB0_56
